# v132 plus static priority raise for waves 4-7 through the P1b unit epilogues (from K-loop exit)
# baseline (speedup 1.0000x reference)
; #define PG8_MFMA_DRAIN() do { if constexpr (FP8) asm volatile("s_nop 15\n\ts_nop 7" ::: "memory"); } while (0)
; #define PG8_BAR __builtin_amdgcn_s_barrier()
; template <class Epi, class Sched, bool ALIGN_EPI = false, bool SP2 = false, bool FP8 = false>
; __device__ __forceinline__ void gemm_phase(PG8_LAS unsigned char* lds, const Gemm g, const Sched& S, const Epi& E) {
;     ...
;         if constexpr (ALIGN_EPI) { if (wr == 0) PG8_BAR; }
;         PG8_MFMA_DRAIN();
;         if constexpr (!Epi::AFTER_DRAIN) { E(acc, cur, wr, wc, fr, fq); S.done(cur); }
.LBB0_333:
	s_nop 15
	s_nop 7
	s_lshl_b32 s47, s0, 8
	v_readfirstlane_b32 s1, v0
	s_nop 3
	s_bitcmp1_b32 s1, 8
	s_cbranch_scc0 .Lp1e_lo
	s_setprio 1
.Lp1e_lo:
	s_cmp_lt_i32 s66, 9
	s_mov_b64 s[0:1], -1
	s_cbranch_scc1 .LBB0_336
	s_and_b64 vcc, exec, s[0:1]
	s_cbranch_vccnz .LBB0_342
